# convrot2 + halo row-pair LayerNorm split across the 11 workgroups of a row block (write-through stores, per-row-block arrival counter) in phases 7 and 15
# speedup vs baseline: 1.0145x; 1.0020x over previous
;     constexpr int NR = 2 * NP;
;     auto rowof = [](int pi) { return SEL == 0 ? 2 * pi : SEL == 1 ? 64 * pi + 62 : 64 * (pi / 31) + 2 * (pi % 31); };
;     auto rowr = [&](int pi, int r) { const int pp = pi + (r >> 1) * pstep; return rowof(pp < p1 ? pp : pi) + (r & 1); };
;     pg8::u32x4 raw[NR][2];
;     if (p0 < p1) {
; #pragma unroll
;         for (int r = 0; r < NR; ++r) { const bf16_t* p = z + (size_t)rowr(p0, r) * DM;
; #pragma unroll
;             for (int j = 0; j < 2; ++j) raw[r][j] = *(const pg8::u32x4*)(p + 8 * lane + 512 * j); } }
;     for (int pi = p0; pi < p1; pi += NP * pstep) {
;         int row[NR];
; #pragma unroll
;         for (int r = 0; r < NR; ++r) row[r] = rowr(pi, r);
;         f32x4 v[NR][4]; float s[NR];
; #pragma unroll
;         for (int r = 0; r < NR; ++r) { s[r] = 0.f;
; #pragma unroll
;             for (int j = 0; j < 2; ++j) {
;                 v[r][2 * j][0] = __builtin_bit_cast(float, raw[r][j].x << 16); v[r][2 * j][1] = __builtin_bit_cast(float, raw[r][j].x & 0xffff0000u);
;                 v[r][2 * j][2] = __builtin_bit_cast(float, raw[r][j].y << 16); v[r][2 * j][3] = __builtin_bit_cast(float, raw[r][j].y & 0xffff0000u);
;                 v[r][2 * j + 1][0] = __builtin_bit_cast(float, raw[r][j].z << 16); v[r][2 * j + 1][1] = __builtin_bit_cast(float, raw[r][j].z & 0xffff0000u);
;                 v[r][2 * j + 1][2] = __builtin_bit_cast(float, raw[r][j].w << 16); v[r][2 * j + 1][3] = __builtin_bit_cast(float, raw[r][j].w & 0xffff0000u); } }
;         { const int nxt = pi + NP * pstep, pq = nxt < p1 ? nxt : pi;
; #pragma unroll
;           for (int r = 0; r < NR; ++r) { const bf16_t* pn = z + (size_t)rowr(pq, r) * DM;
; #pragma unroll
;               for (int j = 0; j < 2; ++j) raw[r][j] = *(const pg8::u32x4*)(pn + 8 * lane + 512 * j); } }
; #pragma unroll
;         for (int r = 0; r < NR; ++r)
; #pragma unroll
;             for (int j = 0; j < 4; ++j) s[r] += (v[r][j][0] + v[r][j][1]) + (v[r][j][2] + v[r][j][3]);
;         float mean[NR], q[NR], rstd[NR];
; #pragma unroll
; __global__ void __launch_bounds__(NWAVES * 64, 2) fwd_mega(Args args) {
;     ...
;         } else {
;             const int pm_ = (int)blockIdx.x / 11;
;             ln_rows_range<1, 1>(ZB, XB, nullptr, STATS, IN(21), IN(22), 64 * pm_ + wave, 64 * pm_ + 64, NWAVES, lane);
.LBB0_670:
	s_or_b64 exec, exec, s[6:7]
	v_readlane_b32 s0, v253, 2
	v_readlane_b32 s1, v253, 3
	s_add_u32 s58, s0, 0x12800000
	s_addc_u32 s59, s1, 0
	s_waitcnt lgkmcnt(0)
	v_mov_b32_e32 v1, v0
	s_add_u32 s16, s0, 0x1f000000
	s_barrier
	s_addc_u32 s17, s1, 0
	v_readfirstlane_b32 s4, v1
	s_ashr_i32 s38, s4, 6
	v_readlane_b32 s0, v253, 0
	s_cmpk_lt_i32 s0, 0x58
	s_cselect_b64 s[60:61], -1, 0
	v_and_b32_e32 v145, 63, v1
	s_mov_b64 s[6:7], -1
	s_and_b64 vcc, exec, s[60:61]
	s_mul_hi_i32 s54, s0, 0x2e8ba2e9
	v_readlane_b32 s1, v253, 1
	s_cbranch_vccz .LBB0_687
	s_lshr_b32 s0, s54, 31
	s_ashr_i32 s3, s54, 1
	s_add_i32 s3, s3, s0
	s_cmp_gt_i32 s38, 63
	s_cbranch_scc1 .LBB0_680
	s_lshl_b32 s2, s3, 6
	v_readlane_b32 s0, v253, 4
	s_add_i32 s19, s38, s2
	v_readlane_b32 s98, v253, 0
	s_mul_i32 s99, s3, 11
	s_sub_i32 s98, s98, s99
	s_mul_i32 s99, s38, 11
	s_add_i32 s98, s98, s99
	s_add_i32 s19, s2, s98
	s_cmp_gt_i32 s98, 63
	s_cbranch_scc1 .LBB0_680
	v_readlane_b32 s1, v253, 5
	s_lshl_b32 s5, s19, 6
	s_load_dwordx4 s[8:11], s[0:1], 0xa8
	s_or_b32 s0, s5, 62
	v_readlane_b32 s6, v253, 21
	s_waitcnt vmcnt(5)
	v_lshlrev_b32_e32 v54, 4, v145
	v_mov_b32_e32 v55, 0
	v_readlane_b32 s7, v253, 22
	s_ashr_i32 s1, s0, 31
	s_lshl_b64 s[0:1], s[0:1], 11
	v_lshl_add_u64 v[50:51], s[6:7], 0, v[54:55]
	v_lshl_add_u64 v[2:3], v[50:51], 0, s[0:1]
	s_or_b32 s0, s5, 63
	s_ashr_i32 s1, s0, 31
	s_lshl_b64 s[0:1], s[0:1], 11
	global_load_dwordx4 v[38:41], v[2:3], off
	global_load_dwordx4 v[42:45], v[2:3], off offset:1024
	v_lshl_add_u64 v[2:3], v[50:51], 0, s[0:1]
	v_lshlrev_b32_e32 v52, 5, v145
	global_load_dwordx4 v[34:37], v[2:3], off
	global_load_dwordx4 v[46:49], v[2:3], off offset:1024
	s_waitcnt lgkmcnt(0)
	global_load_dwordx4 v[2:5], v52, s[8:9] offset:16
	global_load_dwordx4 v[6:9], v52, s[10:11] offset:16
	global_load_dwordx4 v[10:13], v52, s[8:9]
	global_load_dwordx4 v[14:17], v52, s[10:11]
	global_load_dwordx4 v[18:21], v52, s[8:9] offset:2064
	global_load_dwordx4 v[22:25], v52, s[10:11] offset:2064
	global_load_dwordx4 v[26:29], v52, s[8:9] offset:2048
	global_load_dwordx4 v[30:33], v52, s[10:11] offset:2048
	v_readlane_b32 s0, v253, 23
	v_readlane_b32 s1, v253, 24
	s_mov_b32 s5, 0
	v_mov_b32_e32 v93, 0x3727c5ac
	v_lshl_add_u64 v[52:53], s[0:1], 0, v[54:55]
	v_or_b32_e32 v54, 0x400, v54
	v_lshl_add_u64 v[54:55], s[0:1], 0, v[54:55]
	s_lshl_b32 s0, s19, 6
	s_or_b32 s10, s0, 63
	s_mov_b32 s18, 0xf800000
	v_mov_b32_e32 v95, 0x260
	s_branch .LBB0_674
.LBB0_673:
	s_or_b64 exec, exec, s[6:7]
	s_add_i32 s0, s10, -1
	v_pk_mul_f32 v[74:75], v[74:75], v[94:95] op_sel_hi:[1,0]
	v_pk_mul_f32 v[72:73], v[72:73], v[94:95] op_sel_hi:[1,0]
	v_pk_mul_f32 v[76:77], v[80:81], v[94:95] op_sel_hi:[1,0]
	v_pk_mul_f32 v[78:79], v[78:79], v[94:95] op_sel_hi:[1,0]
	s_ashr_i32 s1, s0, 31
	s_waitcnt vmcnt(8)
	v_pk_fma_f32 v[74:75], v[12:13], v[74:75], v[16:17]
	v_pk_fma_f32 v[72:73], v[10:11], v[72:73], v[14:15]
	v_pk_fma_f32 v[76:77], v[4:5], v[76:77], v[8:9]
	v_pk_fma_f32 v[78:79], v[2:3], v[78:79], v[6:7]
	s_lshl_b64 s[0:1], s[0:1], 11
	v_cvt_pk_bf16_f32 v72, v72, v73
	v_cvt_pk_bf16_f32 v73, v74, v75
	v_cvt_pk_bf16_f32 v74, v78, v79
	v_cvt_pk_bf16_f32 v75, v76, v77
	v_lshl_add_u64 v[76:77], v[52:53], 0, s[0:1]
	global_store_dwordx4 v[76:77], v[72:75], off sc0 sc1
	v_pk_mul_f32 v[78:79], v[86:87], v[92:93] op_sel_hi:[1,0]
	s_ashr_i32 s11, s10, 31
	v_pk_mul_f32 v[72:73], v[84:85], v[92:93] op_sel_hi:[1,0]
	v_pk_mul_f32 v[74:75], v[82:83], v[92:93] op_sel_hi:[1,0]
	v_pk_fma_f32 v[76:77], v[12:13], v[72:73], v[16:17]
	v_pk_fma_f32 v[72:73], v[10:11], v[74:75], v[14:15]
	v_pk_mul_f32 v[74:75], v[88:89], v[92:93] op_sel_hi:[1,0]
	s_lshl_b64 s[6:7], s[10:11], 11
	v_pk_fma_f32 v[80:81], v[4:5], v[74:75], v[8:9]
	v_pk_fma_f32 v[74:75], v[2:3], v[78:79], v[6:7]
	v_cvt_pk_bf16_f32 v72, v72, v73
	v_cvt_pk_bf16_f32 v73, v76, v77
	v_cvt_pk_bf16_f32 v74, v74, v75
	v_cvt_pk_bf16_f32 v75, v80, v81
	v_lshl_add_u64 v[76:77], v[52:53], 0, s[6:7]
	v_pk_mul_f32 v[70:71], v[70:71], v[94:95] op_sel_hi:[1,0]
	v_pk_mul_f32 v[68:69], v[68:69], v[94:95] op_sel_hi:[1,0]
	v_pk_mul_f32 v[66:67], v[66:67], v[94:95] op_sel_hi:[1,0]
	v_pk_mul_f32 v[64:65], v[64:65], v[94:95] op_sel_hi:[1,0]
	global_store_dwordx4 v[76:77], v[72:75], off sc0 sc1
	s_waitcnt vmcnt(6)
	v_pk_fma_f32 v[70:71], v[28:29], v[70:71], v[32:33]
	v_pk_fma_f32 v[68:69], v[26:27], v[68:69], v[30:31]
	v_pk_fma_f32 v[72:73], v[20:21], v[66:67], v[24:25]
	v_pk_fma_f32 v[66:67], v[18:19], v[64:65], v[22:23]
	v_cvt_pk_bf16_f32 v64, v68, v69
	v_cvt_pk_bf16_f32 v65, v70, v71
	v_cvt_pk_bf16_f32 v66, v66, v67
	v_cvt_pk_bf16_f32 v67, v72, v73
	v_lshl_add_u64 v[68:69], v[54:55], 0, s[0:1]
	v_pk_mul_f32 v[62:63], v[62:63], v[92:93] op_sel_hi:[1,0]
	v_pk_mul_f32 v[58:59], v[58:59], v[92:93] op_sel_hi:[1,0]
	v_pk_mul_f32 v[60:61], v[60:61], v[92:93] op_sel_hi:[1,0]
	v_pk_mul_f32 v[56:57], v[56:57], v[92:93] op_sel_hi:[1,0]
	global_store_dwordx4 v[68:69], v[64:67], off sc0 sc1
	v_pk_fma_f32 v[62:63], v[28:29], v[62:63], v[32:33]
	v_pk_fma_f32 v[58:59], v[26:27], v[58:59], v[30:31]
	v_pk_fma_f32 v[60:61], v[20:21], v[60:61], v[24:25]
	v_pk_fma_f32 v[64:65], v[18:19], v[56:57], v[22:23]
	v_cvt_pk_bf16_f32 v56, v58, v59
	v_cvt_pk_bf16_f32 v57, v62, v63
	v_cvt_pk_bf16_f32 v58, v64, v65
	v_cvt_pk_bf16_f32 v59, v60, v61
	v_lshl_add_u64 v[60:61], v[54:55], 0, s[6:7]
	s_andn2_b64 vcc, exec, s[12:13]
	s_addk_i32 s10, 0x200
	global_store_dwordx4 v[60:61], v[56:59], off sc0 sc1
	s_cbranch_vccz .LBB0_680

; __global__ void __launch_bounds__(NWAVES * 64, 2) fwd_mega(Args args) {
;     ...
;             asm volatile("s_waitcnt vmcnt(0)" ::: "memory");
;             __syncthreads();
;             if (threadIdx.x == 0) { __builtin_amdgcn_fence(__ATOMIC_ACQUIRE, "agent"); asm volatile("s_waitcnt vmcnt(0)" ::: "memory"); }
;             __syncthreads();
.LBB0_680:
	s_waitcnt vmcnt(0)
	s_barrier
	s_mov_b64 s[6:7], exec
	v_readlane_b32 s0, v253, 12
	v_readlane_b32 s1, v253, 13
	s_and_b64 s[0:1], s[6:7], s[0:1]
	s_mov_b64 exec, s[0:1]
	s_cbranch_execz .LBB0_682
	s_waitcnt vmcnt(0)
	v_readlane_b32 s98, v253, 2
	v_readlane_b32 s99, v253, 3
	s_lshl_b32 s100, s3, 8
	s_add_i32 s100, s100, 0xe000
	s_add_u32 s98, s98, s100
	s_addc_u32 s99, s99, 0
	v_mov_b32_e32 v251, 0
	v_mov_b32_e32 v252, 1
	global_atomic_add v251, v252, s[98:99]
	s_waitcnt vmcnt(0)
	s_movk_i32 s100, 0x1000
.Lhsync_spin_7:
	global_load_dword v252, v251, s[98:99] sc1
	s_waitcnt vmcnt(0)
	v_readfirstlane_b32 s101, v252
	s_cmp_ge_u32 s101, 11
	s_cbranch_scc1 .Lhsync_done_7
	s_sleep 2
	s_sub_u32 s100, s100, 1
	s_cmp_lg_u32 s100, 0
	s_cbranch_scc1 .Lhsync_spin_7
.Lhsync_done_7:
	buffer_inv sc1
	s_waitcnt vmcnt(0)

;     constexpr int NR = 2 * NP;
;     auto rowof = [](int pi) { return SEL == 0 ? 2 * pi : SEL == 1 ? 64 * pi + 62 : 64 * (pi / 31) + 2 * (pi % 31); };
;     auto rowr = [&](int pi, int r) { const int pp = pi + (r >> 1) * pstep; return rowof(pp < p1 ? pp : pi) + (r & 1); };
;     pg8::u32x4 raw[NR][2];
;     if (p0 < p1) {
; #pragma unroll
;         for (int r = 0; r < NR; ++r) { const bf16_t* p = z + (size_t)rowr(p0, r) * DM;
; #pragma unroll
;             for (int j = 0; j < 2; ++j) raw[r][j] = *(const pg8::u32x4*)(p + 8 * lane + 512 * j); } }
;     for (int pi = p0; pi < p1; pi += NP * pstep) {
;         int row[NR];
; #pragma unroll
;         for (int r = 0; r < NR; ++r) row[r] = rowr(pi, r);
;         f32x4 v[NR][4]; float s[NR];
; #pragma unroll
;         for (int r = 0; r < NR; ++r) { s[r] = 0.f;
; #pragma unroll
;             for (int j = 0; j < 2; ++j) {
;                 v[r][2 * j][0] = __builtin_bit_cast(float, raw[r][j].x << 16); v[r][2 * j][1] = __builtin_bit_cast(float, raw[r][j].x & 0xffff0000u);
;                 v[r][2 * j][2] = __builtin_bit_cast(float, raw[r][j].y << 16); v[r][2 * j][3] = __builtin_bit_cast(float, raw[r][j].y & 0xffff0000u);
;                 v[r][2 * j + 1][0] = __builtin_bit_cast(float, raw[r][j].z << 16); v[r][2 * j + 1][1] = __builtin_bit_cast(float, raw[r][j].z & 0xffff0000u);
;                 v[r][2 * j + 1][2] = __builtin_bit_cast(float, raw[r][j].w << 16); v[r][2 * j + 1][3] = __builtin_bit_cast(float, raw[r][j].w & 0xffff0000u); } }
;         { const int nxt = pi + NP * pstep, pq = nxt < p1 ? nxt : pi;
; #pragma unroll
;           for (int r = 0; r < NR; ++r) { const bf16_t* pn = z + (size_t)rowr(pq, r) * DM;
; #pragma unroll
;               for (int j = 0; j < 2; ++j) raw[r][j] = *(const pg8::u32x4*)(pn + 8 * lane + 512 * j); } }
; #pragma unroll
;         for (int r = 0; r < NR; ++r)
; #pragma unroll
;             for (int j = 0; j < 4; ++j) s[r] += (v[r][j][0] + v[r][j][1]) + (v[r][j][2] + v[r][j][3]);
;         float mean[NR], q[NR], rstd[NR];
; #pragma unroll
; __global__ void __launch_bounds__(NWAVES * 64, 2) fwd_mega(Args args) {
;     ...
;         } else {
;             const int pm_ = (int)blockIdx.x / 11;
;             ln_rows_range<1, 1>(ZB, XB, nullptr, STATS, IN(35), IN(36), 64 * pm_ + wave, 64 * pm_ + 64, NWAVES, lane);
.LBB0_1742:
	s_or_b64 exec, exec, s[8:9]
	v_mov_b32_e32 v93, v0
	s_waitcnt lgkmcnt(0)
	s_barrier
	s_mov_b64 s[8:9], -1
	v_readfirstlane_b32 s4, v93
	v_and_b32_e32 v1, 63, v93
	s_ashr_i32 s6, s4, 6
	s_and_b64 vcc, exec, s[60:61]
	s_cbranch_vccz .LBB0_1759
	s_lshr_b32 s0, s54, 31
	s_ashr_i32 s7, s54, 1
	s_add_i32 s7, s7, s0
	s_cmp_gt_i32 s6, 63
	s_cbranch_scc1 .LBB0_1752
	s_lshl_b32 s2, s7, 6
	v_readlane_b32 s0, v253, 4
	s_add_i32 s15, s6, s2
	v_readlane_b32 s98, v253, 0
	s_mul_i32 s99, s7, 11
	s_sub_i32 s98, s98, s99
	s_mul_i32 s99, s6, 11
	s_add_i32 s98, s98, s99
	s_add_i32 s15, s2, s98
	s_cmp_gt_i32 s98, 63
	s_cbranch_scc1 .LBB0_1752
	v_readlane_b32 s1, v253, 5
	s_lshl_b32 s3, s15, 6
	s_load_dwordx4 s[8:11], s[0:1], 0x118
	s_or_b32 s0, s3, 62
	v_readlane_b32 s12, v253, 21
	v_lshlrev_b32_e32 v54, 4, v1
	v_mov_b32_e32 v55, 0
	v_readlane_b32 s13, v253, 22
	s_ashr_i32 s1, s0, 31
	s_lshl_b64 s[0:1], s[0:1], 11
	v_lshl_add_u64 v[50:51], s[12:13], 0, v[54:55]
	v_lshl_add_u64 v[2:3], v[50:51], 0, s[0:1]
	s_or_b32 s0, s3, 63
	s_ashr_i32 s1, s0, 31
	s_lshl_b64 s[0:1], s[0:1], 11
	global_load_dwordx4 v[38:41], v[2:3], off
	global_load_dwordx4 v[42:45], v[2:3], off offset:1024
	v_lshl_add_u64 v[2:3], v[50:51], 0, s[0:1]
	v_lshlrev_b32_e32 v52, 5, v1
	global_load_dwordx4 v[34:37], v[2:3], off
	global_load_dwordx4 v[46:49], v[2:3], off offset:1024
	s_waitcnt lgkmcnt(0)
	global_load_dwordx4 v[2:5], v52, s[8:9] offset:16
	global_load_dwordx4 v[6:9], v52, s[10:11] offset:16
	global_load_dwordx4 v[10:13], v52, s[8:9]
	global_load_dwordx4 v[14:17], v52, s[10:11]
	global_load_dwordx4 v[18:21], v52, s[8:9] offset:2064
	global_load_dwordx4 v[22:25], v52, s[10:11] offset:2064
	global_load_dwordx4 v[26:29], v52, s[8:9] offset:2048
	global_load_dwordx4 v[30:33], v52, s[10:11] offset:2048
	v_readlane_b32 s0, v253, 23
	v_readlane_b32 s1, v253, 24
	s_mov_b32 s5, 0
	v_mov_b32_e32 v95, 0x3727c5ac
	v_lshl_add_u64 v[52:53], s[0:1], 0, v[54:55]
	v_or_b32_e32 v54, 0x400, v54
	v_lshl_add_u64 v[54:55], s[0:1], 0, v[54:55]
	s_lshl_b32 s0, s15, 6
	s_or_b32 s12, s0, 63
	s_mov_b32 s14, 0xf800000
	v_mov_b32_e32 v96, 0x260
	s_branch .LBB0_1746
.LBB0_1745:
	s_or_b64 exec, exec, s[8:9]
	s_add_i32 s0, s12, -1
	v_pk_mul_f32 v[74:75], v[74:75], v[94:95] op_sel_hi:[1,0]
	v_pk_mul_f32 v[72:73], v[72:73], v[94:95] op_sel_hi:[1,0]
	v_pk_mul_f32 v[76:77], v[80:81], v[94:95] op_sel_hi:[1,0]
	v_pk_mul_f32 v[78:79], v[78:79], v[94:95] op_sel_hi:[1,0]
	s_ashr_i32 s1, s0, 31
	s_waitcnt vmcnt(8)
	v_pk_fma_f32 v[74:75], v[12:13], v[74:75], v[16:17]
	v_pk_fma_f32 v[72:73], v[10:11], v[72:73], v[14:15]
	v_pk_fma_f32 v[76:77], v[4:5], v[76:77], v[8:9]
	v_pk_fma_f32 v[78:79], v[2:3], v[78:79], v[6:7]
	s_lshl_b64 s[0:1], s[0:1], 11
	v_cvt_pk_bf16_f32 v72, v72, v73
	v_cvt_pk_bf16_f32 v73, v74, v75
	v_cvt_pk_bf16_f32 v74, v78, v79
	v_cvt_pk_bf16_f32 v75, v76, v77
	v_lshl_add_u64 v[76:77], v[52:53], 0, s[0:1]
	global_store_dwordx4 v[76:77], v[72:75], off sc0 sc1
	v_pk_mul_f32 v[78:79], v[86:87], v[92:93] op_sel_hi:[1,0]
	s_ashr_i32 s13, s12, 31
	v_pk_mul_f32 v[72:73], v[84:85], v[92:93] op_sel_hi:[1,0]
	v_pk_mul_f32 v[74:75], v[82:83], v[92:93] op_sel_hi:[1,0]
	v_pk_fma_f32 v[76:77], v[12:13], v[72:73], v[16:17]
	v_pk_fma_f32 v[72:73], v[10:11], v[74:75], v[14:15]
	v_pk_mul_f32 v[74:75], v[88:89], v[92:93] op_sel_hi:[1,0]
	s_lshl_b64 s[2:3], s[12:13], 11
	v_pk_fma_f32 v[80:81], v[4:5], v[74:75], v[8:9]
	v_pk_fma_f32 v[74:75], v[2:3], v[78:79], v[6:7]
	v_cvt_pk_bf16_f32 v72, v72, v73
	v_cvt_pk_bf16_f32 v73, v76, v77
	v_cvt_pk_bf16_f32 v74, v74, v75
	v_cvt_pk_bf16_f32 v75, v80, v81
	v_lshl_add_u64 v[76:77], v[52:53], 0, s[2:3]
	v_pk_mul_f32 v[70:71], v[70:71], v[94:95] op_sel_hi:[1,0]
	v_pk_mul_f32 v[68:69], v[68:69], v[94:95] op_sel_hi:[1,0]
	v_pk_mul_f32 v[66:67], v[66:67], v[94:95] op_sel_hi:[1,0]
	v_pk_mul_f32 v[64:65], v[64:65], v[94:95] op_sel_hi:[1,0]
	global_store_dwordx4 v[76:77], v[72:75], off sc0 sc1
	s_waitcnt vmcnt(6)
	v_pk_fma_f32 v[70:71], v[28:29], v[70:71], v[32:33]
	v_pk_fma_f32 v[68:69], v[26:27], v[68:69], v[30:31]
	v_pk_fma_f32 v[72:73], v[20:21], v[66:67], v[24:25]
	v_pk_fma_f32 v[66:67], v[18:19], v[64:65], v[22:23]
	v_cvt_pk_bf16_f32 v64, v68, v69
	v_cvt_pk_bf16_f32 v65, v70, v71
	v_cvt_pk_bf16_f32 v66, v66, v67
	v_cvt_pk_bf16_f32 v67, v72, v73
	v_lshl_add_u64 v[68:69], v[54:55], 0, s[0:1]
	v_pk_mul_f32 v[62:63], v[62:63], v[92:93] op_sel_hi:[1,0]
	v_pk_mul_f32 v[58:59], v[58:59], v[92:93] op_sel_hi:[1,0]
	v_pk_mul_f32 v[60:61], v[60:61], v[92:93] op_sel_hi:[1,0]
	v_pk_mul_f32 v[56:57], v[56:57], v[92:93] op_sel_hi:[1,0]
	global_store_dwordx4 v[68:69], v[64:67], off sc0 sc1
	v_pk_fma_f32 v[62:63], v[28:29], v[62:63], v[32:33]
	v_pk_fma_f32 v[58:59], v[26:27], v[58:59], v[30:31]
	v_pk_fma_f32 v[60:61], v[20:21], v[60:61], v[24:25]
	v_pk_fma_f32 v[64:65], v[18:19], v[56:57], v[22:23]
	v_cvt_pk_bf16_f32 v56, v58, v59
	v_cvt_pk_bf16_f32 v57, v62, v63
	v_cvt_pk_bf16_f32 v58, v64, v65
	v_cvt_pk_bf16_f32 v59, v60, v61
	v_lshl_add_u64 v[60:61], v[54:55], 0, s[2:3]
	s_andn2_b64 vcc, exec, s[20:21]
	s_addk_i32 s12, 0x200
	global_store_dwordx4 v[60:61], v[56:59], off sc0 sc1
	s_cbranch_vccz .LBB0_1752

; __global__ void __launch_bounds__(NWAVES * 64, 2) fwd_mega(Args args) {
;     ...
;             asm volatile("s_waitcnt vmcnt(0)" ::: "memory");
;             __syncthreads();
;             if (threadIdx.x == 0) { __builtin_amdgcn_fence(__ATOMIC_ACQUIRE, "agent"); asm volatile("s_waitcnt vmcnt(0)" ::: "memory"); }
;             __syncthreads();
.LBB0_1752:
	s_waitcnt vmcnt(0)
	s_barrier
	s_mov_b64 s[8:9], exec
	v_readlane_b32 s0, v253, 12
	v_readlane_b32 s1, v253, 13
	s_and_b64 s[0:1], s[8:9], s[0:1]
	s_mov_b64 exec, s[0:1]
	s_cbranch_execz .LBB0_1754
	s_waitcnt vmcnt(0)
	v_readlane_b32 s98, v253, 2
	v_readlane_b32 s99, v253, 3
	s_lshl_b32 s100, s7, 8
	s_add_i32 s100, s100, 0xf000
	s_add_u32 s98, s98, s100
	s_addc_u32 s99, s99, 0
	v_mov_b32_e32 v251, 0
	v_mov_b32_e32 v252, 1
	global_atomic_add v251, v252, s[98:99]
	s_waitcnt vmcnt(0)
	s_movk_i32 s100, 0x1000

; __global__ void __launch_bounds__(NWAVES * 64, 2) fwd_mega(Args args) {
	.amdhsa_kernel _Z8fwd_mega4Args
		.amdhsa_group_segment_fixed_size 0
		.amdhsa_private_segment_fixed_size 0
		.amdhsa_kernarg_size 616
		.amdhsa_user_sgpr_count 2
		.amdhsa_user_sgpr_dispatch_ptr 0
		.amdhsa_user_sgpr_queue_ptr 0
		.amdhsa_user_sgpr_kernarg_segment_ptr 1
		.amdhsa_user_sgpr_dispatch_id 0
		.amdhsa_user_sgpr_kernarg_preload_length 0
		.amdhsa_user_sgpr_kernarg_preload_offset 0
		.amdhsa_user_sgpr_private_segment_size 0
		.amdhsa_uses_dynamic_stack 0
		.amdhsa_enable_private_segment 0
		.amdhsa_system_sgpr_workgroup_id_x 1
		.amdhsa_system_sgpr_workgroup_id_y 0
		.amdhsa_system_sgpr_workgroup_id_z 0
		.amdhsa_system_sgpr_workgroup_info 0
		.amdhsa_system_vgpr_workitem_id 0
		.amdhsa_next_free_vgpr 256
		.amdhsa_next_free_sgpr 102
		.amdhsa_accum_offset 256
		.amdhsa_reserve_vcc 1
		.amdhsa_float_round_mode_32 0
		.amdhsa_float_round_mode_16_64 0
		.amdhsa_float_denorm_mode_32 3
		.amdhsa_float_denorm_mode_16_64 3
		.amdhsa_dx10_clamp 1
		.amdhsa_ieee_mode 1
		.amdhsa_fp16_overflow 0
		.amdhsa_tg_split 0
		.amdhsa_exception_fp_ieee_invalid_op 0
		.amdhsa_exception_fp_denorm_src 0
		.amdhsa_exception_fp_ieee_div_zero 0
		.amdhsa_exception_fp_ieee_overflow 0
		.amdhsa_exception_fp_ieee_underflow 0
		.amdhsa_exception_fp_ieee_inexact 0
		.amdhsa_exception_int_div_zero 0
	.end_amdhsa_kernel

; __global__ void __launch_bounds__(NWAVES * 64, 2) fwd_mega(Args args) {
amdhsa.kernels:
  - .agpr_count:     0
    .args:
      - .offset:         0
        .size:           360
        .value_kind:     by_value
      - .offset:         360
        .size:           4
        .value_kind:     hidden_block_count_x
      - .offset:         364
        .size:           4
        .value_kind:     hidden_block_count_y
      - .offset:         368
        .size:           4
        .value_kind:     hidden_block_count_z
      - .offset:         372
        .size:           2
        .value_kind:     hidden_group_size_x
      - .offset:         374
        .size:           2
        .value_kind:     hidden_group_size_y
      - .offset:         376
        .size:           2
        .value_kind:     hidden_group_size_z
      - .offset:         378
        .size:           2
        .value_kind:     hidden_remainder_x
      - .offset:         380
        .size:           2
        .value_kind:     hidden_remainder_y
      - .offset:         382
        .size:           2
        .value_kind:     hidden_remainder_z
      - .offset:         400
        .size:           8
        .value_kind:     hidden_global_offset_x
      - .offset:         408
        .size:           8
        .value_kind:     hidden_global_offset_y
      - .offset:         416
        .size:           8
        .value_kind:     hidden_global_offset_z
      - .offset:         424
        .size:           2
        .value_kind:     hidden_grid_dims
      - .offset:         480
        .size:           4
        .value_kind:     hidden_dynamic_lds_size
    .group_segment_fixed_size: 0
    .kernarg_segment_align: 8
    .kernarg_segment_size: 616
    .language:       OpenCL C
    .language_version:
      - 2
      - 0
    .max_flat_workgroup_size: 512
    .name:           _Z8fwd_mega4Args
    .private_segment_fixed_size: 0
    .sgpr_count:     108
    .sgpr_spill_count: 111
    .symbol:         _Z8fwd_mega4Args.kd
    .uniform_work_group_size: 1
    .uses_dynamic_stack: false
    .vgpr_count:     256
    .vgpr_spill_count: 0
    .wavefront_size: 64
